# P8 light items: all 16 per-token FNet-output loads issued at the item top (was one drained round trip per token), on top of the heavy/light mix
# speedup vs baseline: 1.0043x; 1.0043x over previous
.LBB0_777:
	s_lshr_b32 s98, s25, 8
	s_xor_b32 s98, s98, s25
	s_and_b32 s26, s98, 1
	s_and_b32 s8, s19, 0xffffffc0
	v_add_u32_e32 v66, s8, v1
	s_lshl_b32 s0, s26, 11
	s_add_u32 s0, s3, s0
	v_ashrrev_i32_e32 v67, 31, v66
	s_addc_u32 s1, s18, 0
	v_lshlrev_b64 v[96:97], 12, v[66:67]
	v_lshl_add_u64 v[2:3], s[0:1], 0, v[96:97]
	v_lshl_add_u64 v[2:3], v[2:3], 0, v[74:75]
	global_load_dwordx4 v[62:65], v[2:3], off nt
	global_load_dwordx4 v[58:61], v[2:3], off offset:1024 nt
	v_or_b32_e32 v2, 1, v66
	v_ashrrev_i32_e32 v3, 31, v2
	v_lshlrev_b64 v[2:3], 12, v[2:3]
	v_lshl_add_u64 v[2:3], s[0:1], 0, v[2:3]
	v_lshl_add_u64 v[2:3], v[2:3], 0, v[74:75]
	global_load_dwordx4 v[54:57], v[2:3], off nt
	global_load_dwordx4 v[50:53], v[2:3], off offset:1024 nt
	v_or_b32_e32 v2, 2, v66
	v_ashrrev_i32_e32 v3, 31, v2
	v_lshlrev_b64 v[2:3], 12, v[2:3]
	v_lshl_add_u64 v[2:3], s[0:1], 0, v[2:3]
	v_lshl_add_u64 v[2:3], v[2:3], 0, v[74:75]
	global_load_dwordx4 v[46:49], v[2:3], off nt
	global_load_dwordx4 v[42:45], v[2:3], off offset:1024 nt
	v_or_b32_e32 v2, 3, v66
	v_ashrrev_i32_e32 v3, 31, v2
	v_lshlrev_b64 v[2:3], 12, v[2:3]
	v_lshl_add_u64 v[2:3], s[0:1], 0, v[2:3]
	v_lshl_add_u64 v[2:3], v[2:3], 0, v[74:75]
	global_load_dwordx4 v[38:41], v[2:3], off nt
	global_load_dwordx4 v[34:37], v[2:3], off offset:1024 nt
	v_or_b32_e32 v2, 4, v66
	v_ashrrev_i32_e32 v3, 31, v2
	v_lshlrev_b64 v[2:3], 12, v[2:3]
	v_lshl_add_u64 v[2:3], s[0:1], 0, v[2:3]
	v_lshl_add_u64 v[2:3], v[2:3], 0, v[74:75]
	global_load_dwordx4 v[30:33], v[2:3], off nt
	global_load_dwordx4 v[26:29], v[2:3], off offset:1024 nt
	v_or_b32_e32 v2, 5, v66
	v_ashrrev_i32_e32 v3, 31, v2
	v_lshlrev_b64 v[2:3], 12, v[2:3]
	v_lshl_add_u64 v[2:3], s[0:1], 0, v[2:3]
	v_lshl_add_u64 v[2:3], v[2:3], 0, v[74:75]
	global_load_dwordx4 v[22:25], v[2:3], off nt
	global_load_dwordx4 v[18:21], v[2:3], off offset:1024 nt
	v_or_b32_e32 v2, 6, v66
	v_ashrrev_i32_e32 v3, 31, v2
	v_lshlrev_b64 v[2:3], 12, v[2:3]
	v_lshl_add_u64 v[2:3], s[0:1], 0, v[2:3]
	v_lshl_add_u64 v[2:3], v[2:3], 0, v[74:75]
	global_load_dwordx4 v[14:17], v[2:3], off nt
	global_load_dwordx4 v[10:13], v[2:3], off offset:1024 nt
	v_or_b32_e32 v2, 7, v66
	v_ashrrev_i32_e32 v3, 31, v2
	v_lshlrev_b64 v[2:3], 12, v[2:3]
	v_lshl_add_u64 v[2:3], s[0:1], 0, v[2:3]
	v_lshl_add_u64 v[2:3], v[2:3], 0, v[74:75]
	global_load_dwordx4 v[6:9], v[2:3], off nt
	s_nop 0
	global_load_dwordx4 v[2:5], v[2:3], off offset:1024 nt
	s_bitcmp1_b32 s26, 0
	s_cselect_b64 s[10:11], -1, 0
	s_and_b64 vcc, exec, s[10:11]
	s_cbranch_vccz .Lp8_hy
	v_lshlrev_b64 v[222:223], 11, v[66:67]
	v_lshl_add_u64 v[222:223], s[6:7], 0, v[222:223]
	v_lshl_add_u64 v[222:223], v[222:223], 0, v[74:75]
	s_mov_b64 s[100:101], 0x1000
	global_load_dwordx4 v[154:157], v[222:223], off nt
	global_load_dwordx4 v[158:161], v[222:223], off offset:1024 nt
	global_load_dwordx4 v[162:165], v[222:223], off offset:2048 nt
	global_load_dwordx4 v[166:169], v[222:223], off offset:3072 nt
	v_lshl_add_u64 v[222:223], v[222:223], 0, s[100:101]
	global_load_dwordx4 v[170:173], v[222:223], off nt
	global_load_dwordx4 v[174:177], v[222:223], off offset:1024 nt
	global_load_dwordx4 v[178:181], v[222:223], off offset:2048 nt
	global_load_dwordx4 v[182:185], v[222:223], off offset:3072 nt
	v_lshl_add_u64 v[222:223], v[222:223], 0, s[100:101]
	global_load_dwordx4 v[186:189], v[222:223], off nt
	global_load_dwordx4 v[190:193], v[222:223], off offset:1024 nt
	global_load_dwordx4 v[194:197], v[222:223], off offset:2048 nt
	global_load_dwordx4 v[202:205], v[222:223], off offset:3072 nt
	v_lshl_add_u64 v[222:223], v[222:223], 0, s[100:101]
	global_load_dwordx4 v[206:209], v[222:223], off nt
	global_load_dwordx4 v[210:213], v[222:223], off offset:1024 nt
	global_load_dwordx4 v[214:217], v[222:223], off offset:2048 nt
	global_load_dwordx4 v[218:221], v[222:223], off offset:3072 nt
	s_branch .LBB0_779
